# mix_post_b RWKV part in the GLU phase and the final norm's weight loads: loads of a row issued together (cloned address arithmetic)
# speedup vs baseline: 1.0082x; 1.0009x over previous
.LBB0_1609:
	s_cmpk_lt_i32 s6, 0x2040
	s_cselect_b64 s[0:1], -1, 0
	s_cmpk_gt_i32 s6, 0x203f
	v_lshl_add_u64 v[4:5], s[12:13], 0, v[96:97]
	v_lshl_add_u64 v[30:31], s[8:9], 0, v[96:97]
	s_cbranch_scc1 .LBB0_1611
	v_add_co_u32_e32 v98, vcc, 0x33812000, v4
	s_nop 1
	v_addc_co_u32_e32 v99, vcc, 0, v5, vcc
	v_add_co_u32_e32 v100, vcc, 0x326f2000, v4
	global_load_dwordx4 v[102:105], v[98:99], off
	s_nop 1
	v_addc_co_u32_e32 v101, vcc, 0, v5, vcc
	global_load_dwordx4 v[106:109], v[100:101], off
	v_add_co_u32_e32 v100, vcc, s5, v4
	s_nop 1
	v_addc_co_u32_e32 v101, vcc, 0, v5, vcc
	global_load_dwordx4 v[110:113], v[100:101], off
	global_load_dwordx4 v[114:117], v[28:29], off offset:16
	global_load_dwordx4 v[118:121], v[28:29], off
	v_add_co_u32_e32 v0, vcc, 0x33812000, v4
	s_nop 1
	v_addc_co_u32_e32 v1, vcc, 0, v5, vcc
	v_add_co_u32_e32 v6, vcc, 0x326f2000, v4
	s_waitcnt vmcnt(0)
	v_mov_b64_e32 v[0:1], v[102:103]
	v_mov_b64_e32 v[2:3], v[104:105]
	s_nop 0
	v_addc_co_u32_e32 v7, vcc, 0, v5, vcc
	v_mov_b64_e32 v[6:7], v[106:107]
	v_mov_b64_e32 v[8:9], v[108:109]
	s_waitcnt vmcnt(0)
	v_lshlrev_b32_e32 v35, 16, v2
	v_lshlrev_b32_e32 v34, 16, v0
	v_and_b32_e32 v37, 0xffff0000, v2
	v_lshlrev_b32_e32 v18, 16, v6
	v_and_b32_e32 v19, 0xffff0000, v6
	v_add_co_u32_e32 v6, vcc, s5, v4
	v_lshlrev_b32_e32 v20, 16, v7
	v_and_b32_e32 v21, 0xffff0000, v7
	v_addc_co_u32_e32 v7, vcc, 0, v5, vcc
	v_lshlrev_b32_e32 v22, 16, v8
	v_and_b32_e32 v23, 0xffff0000, v8
	v_lshlrev_b32_e32 v32, 16, v9
	v_and_b32_e32 v33, 0xffff0000, v9
	v_mov_b64_e32 v[6:7], v[110:111]
	v_mov_b64_e32 v[8:9], v[112:113]
	s_nop 0
	v_mov_b64_e32 v[10:11], v[114:115]
	v_mov_b64_e32 v[12:13], v[116:117]
	v_mov_b64_e32 v[14:15], v[118:119]
	v_mov_b64_e32 v[16:17], v[120:121]
	v_and_b32_e32 v36, 0xffff0000, v0
	v_lshlrev_b32_e32 v39, 16, v3
	v_lshlrev_b32_e32 v38, 16, v1
	v_and_b32_e32 v2, 0xffff0000, v1
	v_pk_add_f32 v[0:1], v[34:35], v[36:37]
	v_and_b32_e32 v3, 0xffff0000, v3
	v_pk_add_f32 v[0:1], v[0:1], v[38:39]
	s_nop 0
	v_pk_add_f32 v[0:1], v[0:1], v[2:3]
	s_nop 0
	v_add_f32_e32 v0, v0, v1
	ds_bpermute_b32 v1, v50, v0
	s_waitcnt lgkmcnt(0)
	v_add_f32_e32 v0, v0, v1
	ds_bpermute_b32 v1, v51, v0
	s_waitcnt lgkmcnt(0)
	v_add_f32_e32 v0, v0, v1
	ds_bpermute_b32 v1, v52, v0
	s_waitcnt lgkmcnt(0)
	v_add_f32_e32 v0, v0, v1
	v_fmac_f32_e32 v36, 0xbc800000, v0
	v_fmac_f32_e32 v37, 0xbc800000, v0
	v_fmac_f32_e32 v34, 0xbc800000, v0
	v_fmac_f32_e32 v35, 0xbc800000, v0
	v_mov_b32_e32 v1, v37
	v_mov_b32_e32 v41, v36
	v_pk_mul_f32 v[36:37], v[36:37], v[36:37]
	v_fmac_f32_e32 v2, 0xbc800000, v0
	v_fmac_f32_e32 v38, 0xbc800000, v0
	v_fmac_f32_e32 v3, 0xbc800000, v0
	v_fmac_f32_e32 v39, 0xbc800000, v0
	v_mov_b32_e32 v0, v35
	v_mov_b32_e32 v40, v34
	v_pk_fma_f32 v[34:35], v[34:35], v[34:35], v[36:37]
	v_mov_b32_e32 v37, v3
	v_pk_fma_f32 v[34:35], v[38:39], v[38:39], v[34:35]
	v_mov_b32_e32 v43, v2
	v_pk_fma_f32 v[2:3], v[2:3], v[2:3], v[34:35]
	v_mov_b32_e32 v42, v38
	v_add_f32_e32 v2, v2, v3
	ds_bpermute_b32 v3, v50, v2
	v_mov_b32_e32 v36, v39
	s_waitcnt lgkmcnt(0)
	v_add_f32_e32 v2, v2, v3
	ds_bpermute_b32 v3, v51, v2
	s_waitcnt lgkmcnt(0)
	v_add_f32_e32 v2, v2, v3
	ds_bpermute_b32 v3, v52, v2
	s_waitcnt lgkmcnt(0)
	v_add_f32_e32 v2, v2, v3
	v_fmamk_f32 v2, v2, 0x3c800000, v231
	v_cmp_gt_f32_e32 vcc, s45, v2
	v_mul_f32_e32 v3, 0x4b800000, v2
	s_nop 0
	v_cndmask_b32_e32 v2, v2, v3, vcc
	v_rsq_f32_e32 v2, v2
	s_nop 0
	v_mul_f32_e32 v3, 0x45800000, v2
	v_cndmask_b32_e32 v2, v2, v3, vcc
	v_pk_mul_f32 v[34:35], v[42:43], v[2:3] op_sel_hi:[1,0]
	v_pk_mul_f32 v[38:39], v[40:41], v[2:3] op_sel_hi:[1,0]
	s_waitcnt vmcnt(0)
	v_pk_fma_f32 v[16:17], v[16:17], v[34:35], v[20:21]
	v_pk_fma_f32 v[14:15], v[14:15], v[38:39], v[18:19]
	v_pk_mul_f32 v[18:19], v[36:37], v[2:3] op_sel_hi:[1,0]
	v_pk_mul_f32 v[0:1], v[0:1], v[2:3] op_sel_hi:[1,0]
	v_pk_fma_f32 v[2:3], v[12:13], v[18:19], v[32:33]
	v_pk_fma_f32 v[0:1], v[10:11], v[0:1], v[22:23]
	v_lshlrev_b32_e32 v11, 16, v7
	v_lshlrev_b32_e32 v10, 16, v6
	v_mov_b32_e32 v12, v14
	v_mov_b32_e32 v13, v16
	v_pk_mul_f32 v[10:11], v[12:13], v[10:11]
	v_and_b32_e32 v7, 0xffff0000, v7
	v_and_b32_e32 v6, 0xffff0000, v6
	v_mov_b32_e32 v16, v15
	v_lshlrev_b32_e32 v13, 16, v9
	v_lshlrev_b32_e32 v12, 16, v8
	v_mov_b32_e32 v15, v2
	v_and_b32_e32 v9, 0xffff0000, v9
	v_and_b32_e32 v8, 0xffff0000, v8
	v_mov_b32_e32 v2, v1
	v_pk_mul_f32 v[6:7], v[16:17], v[6:7]
	v_mov_b32_e32 v14, v0
	v_pk_mul_f32 v[0:1], v[2:3], v[8:9]
	v_pk_mul_f32 v[12:13], v[14:15], v[12:13]
	v_bfe_u32 v2, v1, 16, 1
	v_bfe_u32 v8, v7, 16, 1
	v_bfe_u32 v3, v0, 16, 1
	v_bfe_u32 v9, v6, 16, 1
	v_add3_u32 v7, v7, v8, s48
	v_add3_u32 v1, v1, v2, s48
	v_bfe_u32 v2, v10, 16, 1
	v_bfe_u32 v8, v12, 16, 1
	v_add3_u32 v6, v6, v9, s48
	v_add3_u32 v0, v0, v3, s48
	v_bfe_u32 v3, v11, 16, 1
	v_bfe_u32 v9, v13, 16, 1
	v_add3_u32 v8, v12, v8, s48
	v_add3_u32 v2, v10, v2, s48
	v_add3_u32 v9, v13, v9, s48
	v_add3_u32 v3, v11, v3, s48
	v_lshrrev_b32_e32 v10, 16, v2
	v_lshrrev_b32_e32 v2, 16, v8
	v_lshrrev_b32_e32 v11, 16, v3
	v_lshrrev_b32_e32 v3, 16, v9
	v_and_or_b32 v2, v0, s36, v2
	v_and_or_b32 v0, v6, s36, v10
	v_add_co_u32_e32 v6, vcc, 0x25500000, v30
	v_and_or_b32 v3, v1, s36, v3
	v_and_or_b32 v1, v7, s36, v11
	v_addc_co_u32_e32 v7, vcc, 0, v31, vcc
	global_store_dwordx4 v[6:7], v[0:3], off

.LBB0_2199:
	s_or_b64 exec, exec, s[8:9]
	global_load_dwordx4 v[100:103], v[16:17], off offset:16
	global_load_dwordx4 v[104:107], v[16:17], off
	global_load_dwordx4 v[108:111], v[16:17], off offset:2048
	global_load_dwordx4 v[112:115], v[16:17], off offset:2064
	global_load_dwordx4 v[116:119], v[18:19], off
	global_load_dwordx4 v[120:123], v[18:19], off offset:16
	global_load_dwordx4 v[124:127], v[20:21], off
	global_load_dwordx4 v[128:131], v[20:21], off offset:16
	v_pk_mul_f32 v[44:45], v[24:25], v[24:25]
	v_pk_mul_f32 v[52:53], v[26:27], v[26:27]
	v_add_f32_e32 v12, v44, v45
	v_add_f32_e32 v12, v52, v12
	v_pk_mul_f32 v[54:55], v[28:29], v[28:29]
	v_add_f32_e32 v12, v53, v12
	v_add_f32_e32 v12, v54, v12
	v_pk_mul_f32 v[56:57], v[30:31], v[30:31]
	v_add_f32_e32 v12, v55, v12
	v_add_f32_e32 v12, v56, v12
	v_pk_mul_f32 v[58:59], v[32:33], v[32:33]
	v_add_f32_e32 v12, v57, v12
	v_add_f32_e32 v12, v12, v58
	v_add_f32_e32 v12, v59, v12
	s_waitcnt vmcnt(0)
	v_mov_b64_e32 v[52:53], v[100:101]
	v_mov_b64_e32 v[54:55], v[102:103]
	v_mov_b64_e32 v[56:57], v[104:105]
	v_mov_b64_e32 v[58:59], v[106:107]
	v_pk_mul_f32 v[60:61], v[8:9], v[8:9]
	v_pk_mul_f32 v[62:63], v[34:35], v[34:35]
	v_add_f32_e32 v12, v60, v12
	v_add_f32_e32 v12, v61, v12
	v_add_f32_e32 v12, v62, v12
	v_pk_mul_f32 v[64:65], v[10:11], v[10:11]
	v_add_f32_e32 v12, v63, v12
	v_add_f32_e32 v12, v64, v12
	v_pk_mul_f32 v[66:67], v[36:37], v[36:37]
	v_add_f32_e32 v12, v65, v12
	v_add_f32_e32 v12, v12, v66
	v_pk_mul_f32 v[68:69], v[4:5], v[4:5]
	v_add_f32_e32 v12, v67, v12
	v_add_f32_e32 v12, v68, v12
	v_pk_mul_f32 v[70:71], v[38:39], v[38:39]
	v_add_f32_e32 v12, v69, v12
	v_add_f32_e32 v12, v70, v12
	v_pk_mul_f32 v[72:73], v[6:7], v[6:7]
	v_add_f32_e32 v12, v71, v12
	v_add_f32_e32 v12, v72, v12
	v_pk_mul_f32 v[74:75], v[40:41], v[40:41]
	v_add_f32_e32 v12, v73, v12
	v_add_f32_e32 v12, v12, v74
	v_pk_mul_f32 v[76:77], v[0:1], v[0:1]
	v_add_f32_e32 v12, v75, v12
	v_add_f32_e32 v12, v76, v12
	v_pk_mul_f32 v[78:79], v[42:43], v[42:43]
	v_add_f32_e32 v12, v77, v12
	v_add_f32_e32 v12, v78, v12
	v_pk_mul_f32 v[80:81], v[2:3], v[2:3]
	v_add_f32_e32 v12, v79, v12
	v_cmp_lt_i32_e32 vcc, v246, v252
	v_add_f32_e32 v12, v80, v12
	v_add_f32_e32 v12, v81, v12
	v_cndmask_b32_e32 v44, v217, v246, vcc
	v_lshlrev_b32_e32 v44, 2, v44
	ds_bpermute_b32 v44, v44, v12
	v_cmp_lt_i32_e32 vcc, v247, v252
	s_waitcnt lgkmcnt(0)
	v_add_f32_e32 v12, v12, v44
	v_cndmask_b32_e32 v44, v217, v247, vcc
	v_lshlrev_b32_e32 v44, 2, v44
	ds_bpermute_b32 v44, v44, v12
	v_cmp_lt_i32_e32 vcc, v248, v252
	s_waitcnt lgkmcnt(0)
	v_add_f32_e32 v12, v12, v44
	v_cndmask_b32_e32 v44, v217, v248, vcc
	v_lshlrev_b32_e32 v44, 2, v44
	ds_bpermute_b32 v44, v44, v12
	v_cmp_lt_i32_e32 vcc, v221, v252
	s_waitcnt lgkmcnt(0)
	v_add_f32_e32 v12, v12, v44
	v_cndmask_b32_e32 v44, v217, v221, vcc
	v_lshlrev_b32_e32 v44, 2, v44
	ds_bpermute_b32 v44, v44, v12
	v_cmp_lt_i32_e32 vcc, v216, v252
	s_waitcnt lgkmcnt(0)
	v_add_f32_e32 v12, v12, v44
	v_cndmask_b32_e32 v44, v217, v216, vcc
	v_lshlrev_b32_e32 v44, 2, v44
	ds_bpermute_b32 v44, v44, v12
	v_cmp_lt_i32_e32 vcc, v218, v252
	s_waitcnt lgkmcnt(0)
	v_add_f32_e32 v12, v12, v44
	v_cndmask_b32_e32 v44, v217, v218, vcc
	v_lshlrev_b32_e32 v44, 2, v44
	ds_bpermute_b32 v44, v44, v12
	s_waitcnt lgkmcnt(0)
	v_add_f32_e32 v12, v12, v44
	v_fmamk_f32 v12, v12, 0x3a000000, v47
	v_mul_f32_e32 v44, 0x4b800000, v12
	v_cmp_gt_f32_e32 vcc, s20, v12
	s_nop 1
	v_cndmask_b32_e32 v12, v12, v44, vcc
	v_rsq_f32_e32 v12, v12
	s_nop 0
	v_mul_f32_e32 v44, 0x45800000, v12
	v_cndmask_b32_e32 v12, v12, v44, vcc
	v_pk_mul_f32 v[24:25], v[24:25], v[12:13] op_sel_hi:[1,0]
	v_pk_mul_f32 v[26:27], v[26:27], v[12:13] op_sel_hi:[1,0]
	s_waitcnt vmcnt(0)
	v_pk_mul_f32 v[24:25], v[56:57], v[24:25]
	v_pk_mul_f32 v[26:27], v[58:59], v[26:27]
	v_pk_mul_f32 v[28:29], v[28:29], v[12:13] op_sel_hi:[1,0]
	v_pk_mul_f32 v[30:31], v[30:31], v[12:13] op_sel_hi:[1,0]
	v_pk_mul_f32 v[28:29], v[52:53], v[28:29]
	v_pk_mul_f32 v[30:31], v[54:55], v[30:31]
	global_store_dwordx4 v48, v[24:27], s[6:7]
	global_store_dwordx4 v48, v[28:31], s[6:7] offset:16
	v_mov_b64_e32 v[24:25], v[108:109]
	v_mov_b64_e32 v[26:27], v[110:111]
	s_nop 0
	v_mov_b64_e32 v[28:29], v[112:113]
	v_mov_b64_e32 v[30:31], v[114:115]
	v_pk_mul_f32 v[32:33], v[32:33], v[12:13] op_sel_hi:[1,0]
	v_pk_mul_f32 v[8:9], v[8:9], v[12:13] op_sel_hi:[1,0]
	v_pk_mul_f32 v[34:35], v[34:35], v[12:13] op_sel_hi:[1,0]
	v_pk_mul_f32 v[44:45], v[10:11], v[12:13] op_sel_hi:[1,0]
	v_pk_mul_f32 v[4:5], v[4:5], v[12:13] op_sel_hi:[1,0]
	v_pk_mul_f32 v[0:1], v[0:1], v[12:13] op_sel_hi:[1,0]
	s_waitcnt vmcnt(1)
	v_pk_mul_f32 v[10:11], v[26:27], v[8:9]
	v_pk_mul_f32 v[8:9], v[24:25], v[32:33]
	s_waitcnt vmcnt(0)
	v_pk_mul_f32 v[26:27], v[30:31], v[44:45]
	v_pk_mul_f32 v[24:25], v[28:29], v[34:35]
	global_store_dwordx4 v48, v[8:11], s[6:7] offset:2048
	global_store_dwordx4 v48, v[24:27], s[6:7] offset:2064
	v_mov_b64_e32 v[8:9], v[116:117]
	v_mov_b64_e32 v[10:11], v[118:119]
	s_nop 0
	v_mov_b64_e32 v[24:25], v[120:121]
	v_mov_b64_e32 v[26:27], v[122:123]
	v_pk_mul_f32 v[28:29], v[36:37], v[12:13] op_sel_hi:[1,0]
	v_pk_mul_f32 v[30:31], v[38:39], v[12:13] op_sel_hi:[1,0]
	v_pk_mul_f32 v[32:33], v[6:7], v[12:13] op_sel_hi:[1,0]
	s_waitcnt vmcnt(1)
	v_pk_mul_f32 v[6:7], v[10:11], v[4:5]
	v_pk_mul_f32 v[4:5], v[8:9], v[28:29]
	s_waitcnt vmcnt(0)
	v_pk_mul_f32 v[10:11], v[26:27], v[32:33]
	v_pk_mul_f32 v[8:9], v[24:25], v[30:31]
	global_store_dwordx4 v49, v[4:7], s[6:7]
	global_store_dwordx4 v49, v[8:11], s[6:7] offset:16
	v_mov_b64_e32 v[4:5], v[124:125]
	v_mov_b64_e32 v[6:7], v[126:127]
	s_nop 0
	v_mov_b64_e32 v[8:9], v[128:129]
	v_mov_b64_e32 v[10:11], v[130:131]
	v_pk_mul_f32 v[24:25], v[40:41], v[12:13] op_sel_hi:[1,0]
	v_pk_mul_f32 v[26:27], v[42:43], v[12:13] op_sel_hi:[1,0]
	v_pk_mul_f32 v[28:29], v[2:3], v[12:13] op_sel_hi:[1,0]
	s_waitcnt vmcnt(1)
	v_pk_mul_f32 v[2:3], v[6:7], v[0:1]
	v_pk_mul_f32 v[0:1], v[4:5], v[24:25]
	s_waitcnt vmcnt(0)
	v_pk_mul_f32 v[6:7], v[10:11], v[28:29]
	v_pk_mul_f32 v[4:5], v[8:9], v[26:27]
	global_store_dwordx4 v50, v[0:3], s[6:7]
	global_store_dwordx4 v50, v[4:7], s[6:7] offset:16
